# swiglu GEMM (phases 4, 9): epilogue deferred into the load segments of the next unit's first K-iteration, in place on the accumulators; alignment barriers skipped on that path
# baseline (speedup 1.0000x reference)
; __device__ __forceinline__ unsigned xb_ld(unsigned* p)              { return __hip_atomic_load(p, __ATOMIC_RELAXED, __HIP_MEMORY_SCOPE_AGENT); }
;     __host__ __device__ bool next(int i, Unit& u) const {
;         if (rev_n) { i = rev_n - 1 - i; if (i < 0) return false; }
;         const long L = (long)i * G + c; if (L >= nwg) return false;
;         int wgid = (int)L; { const int q = nwg / NXCD, r = nwg % NXCD, xcd = wgid % NXCD, off = wgid / NXCD; wgid = (xcd < r ? xcd * (q + 1) : r * (q + 1) + (xcd - r) * q) + off; }
; __device__ __forceinline__ void xcd_barrier_complete(unsigned* bar, unsigned x, unsigned& nloc, unsigned& nx) {
;     const unsigned G = gridDim.x * gridDim.y * gridDim.z;
;     unsigned sum, cnt, mine, sp = 0u;
;     for (;;) {
;         sum = 0u; cnt = 0u; mine = 0u;
; #pragma unroll
;         for (unsigned j = 0; j < 16; ++j) { const unsigned c = xb_ld(&bar[XB_XCNT(j)]); sum += c; cnt += (c > 0u) ? 1u : 0u; mine = (j == x) ? c : mine; }
;         if (sum == G) break;
;         __builtin_amdgcn_s_sleep(1);
;         if ((++sp & 255u) == 0u) { if (xb_ld(&bar[XB_TMO])) break; if (sp > XB_SPIN_CAP) { atomicAdd(&bar[XB_TMO], 1u); break; } }
;     }
;     nloc = mine > 0u ? mine : 1u; nx = cnt > 0u ? cnt : 1u;
.LBB0_5:
	s_or_b64 exec, exec, s[4:5]
	s_cmpk_lt_i32 s2, 0x100
	s_cselect_b64 s[4:5], -1, 0
	v_writelane_b32 v253, s4, 8
	s_cmpk_lt_i32 s2, 0x800
	v_lshrrev_b32_e32 v1, 20, v0
	v_writelane_b32 v253, s5, 9
	s_cselect_b64 s[4:5], -1, 0
	v_writelane_b32 v253, s4, 10
	s_ashr_i32 s3, s2, 31
	s_add_i32 s13, 0, 0x20400
	v_writelane_b32 v253, s5, 11
	s_lshr_b32 s4, s3, 29
	s_add_i32 s4, s2, s4
	s_ashr_i32 s5, s4, 3
	s_and_b32 s4, s4, -8
	s_sub_i32 s6, s2, s4
	s_lshl_b32 s7, s6, 8
	s_cmpk_lt_i32 s2, 0xb00
	s_cselect_b64 s[14:15], -1, 0
	v_writelane_b32 v253, s14, 12
	s_cmpk_lt_i32 s2, 0x200
	v_lshrrev_b32_e32 v0, 10, v0
	v_writelane_b32 v253, s15, 13
	s_cselect_b64 s[14:15], -1, 0
	s_sub_i32 s4, 0x1ff, s2
	v_writelane_b32 v253, s14, 14
	s_cmpk_lt_i32 s2, 0x400
	v_or_b32_e32 v0, v0, v1
	v_writelane_b32 v253, s15, 15
	s_cselect_b64 s[14:15], -1, 0
	v_writelane_b32 v253, s14, 16
	s_lshl_b32 s10, s6, 7
	v_mbcnt_lo_u32_b32 v2, -1, 0
	v_writelane_b32 v253, s15, 17
	s_lshl_b32 s14, s2, 3
	v_writelane_b32 v253, s14, 18
	s_lshl_b32 s14, s2, 9
	v_writelane_b32 v253, s14, 19
	s_add_u32 s14, s0, 0x80200
	s_addc_u32 s15, s1, 0
	s_add_u32 s60, s0, 0x80400
	s_addc_u32 s61, s1, 0
	s_add_u32 s64, s0, 0x80500
	s_addc_u32 s65, s1, 0
	s_add_u32 s70, s0, 0x80600
	s_addc_u32 s71, s1, 0
	s_add_u32 s72, s0, 0x80700
	s_addc_u32 s73, s1, 0
	s_add_u32 s74, s0, 0x80800
	s_addc_u32 s75, s1, 0
	s_add_u32 s76, s0, 0x80900
	s_addc_u32 s77, s1, 0
	s_add_u32 s94, s0, 0x80a00
	s_addc_u32 s95, s1, 0
	s_add_u32 s96, s0, 0x80b00
	s_addc_u32 s97, s1, 0
	s_add_u32 s98, s0, 0x80c00
	v_writelane_b32 v253, s14, 20
	s_addc_u32 s99, s1, 0
	v_writelane_b32 v197, s94, 0
	v_writelane_b32 v253, s15, 21
	s_add_u32 s14, s0, 0x80d00
	s_addc_u32 s15, s1, 0
	v_writelane_b32 v253, s14, 22
	v_writelane_b32 v197, s95, 1
	v_writelane_b32 v197, s96, 2
	v_writelane_b32 v253, s15, 23
	s_add_u32 s14, s0, 0x80e00
	s_addc_u32 s15, s1, 0
	v_writelane_b32 v253, s14, 24
	v_mbcnt_hi_u32_b32 v234, -1, v2
	s_mov_b32 s24, 0xfffe0000
	v_writelane_b32 v253, s15, 25
	s_add_u32 s14, s0, 0x80f00
	s_addc_u32 s15, s1, 0
	v_writelane_b32 v253, s14, 26
	v_writelane_b32 v197, s97, 3
	v_lshl_add_u32 v231, v230, 2, s13
	v_writelane_b32 v253, s15, 27
	s_add_u32 s14, s0, 0x81000
	s_addc_u32 s15, s1, 0
	v_writelane_b32 v253, s14, 28
	v_mov_b32_e32 v1, 0
	v_mov_b32_e32 v232, 0x358637bd
	v_writelane_b32 v253, s15, 29
	s_add_u32 s14, s0, 0x81100
	s_addc_u32 s15, s1, 0
	v_writelane_b32 v253, s14, 30
	v_mov_b32_e32 v244, 1
	v_and_b32_e32 v235, 64, v234
	v_writelane_b32 v253, s15, 31
	s_add_u32 s14, s0, 0x81200
	s_addc_u32 s15, s1, 0
	v_writelane_b32 v253, s14, 32
	v_add_u32_e32 v245, -1, v234
	v_add_u32_e32 v233, -2, v234
	v_writelane_b32 v253, s15, 33
	s_add_u32 s14, s0, 0x81300
	s_addc_u32 s15, s1, 0
	v_writelane_b32 v253, s14, 34
	s_cmp_eq_u32 s11, 15
	v_add_u32_e32 v238, -4, v234
	v_writelane_b32 v253, s15, 35
	s_cselect_b64 s[14:15], -1, 0
	v_writelane_b32 v253, s14, 36
	s_cmp_eq_u32 s11, 14
	v_add_u32_e32 v239, -8, v234
	v_writelane_b32 v253, s15, 37
	s_cselect_b64 s[14:15], -1, 0
	v_writelane_b32 v253, s14, 38
	s_cmp_eq_u32 s11, 13
	v_add_u32_e32 v240, -16, v234
	v_writelane_b32 v253, s15, 39
	s_cselect_b64 s[14:15], -1, 0
	v_writelane_b32 v253, s14, 40
	s_cmp_eq_u32 s11, 12
	v_subrev_u32_e32 v196, 32, v234
	v_writelane_b32 v253, s15, 41
	s_cselect_b64 s[14:15], -1, 0
	v_writelane_b32 v253, s14, 42
	s_cmp_eq_u32 s11, 11
	v_mov_b32_e32 v242, 0xff800000
	v_writelane_b32 v253, s15, 43
	s_cselect_b64 s[14:15], -1, 0
	v_writelane_b32 v253, s14, 44
	s_cmp_eq_u32 s11, 10
	v_mov_b32_e32 v243, 0x7f800000
	v_writelane_b32 v253, s15, 45
	s_cselect_b64 s[14:15], -1, 0
	v_writelane_b32 v253, s14, 46
	s_cmp_eq_u32 s11, 9
	v_writelane_b32 v253, s15, 47
	s_cselect_b64 s[14:15], -1, 0
	v_writelane_b32 v253, s14, 48
	s_cmp_eq_u32 s11, 8
	v_writelane_b32 v253, s15, 49
	s_cselect_b64 s[14:15], -1, 0
	v_writelane_b32 v253, s14, 50
	s_cmp_eq_u32 s11, 7
	s_mov_b32 s67, 0x42200000
	v_writelane_b32 v253, s15, 51
	s_cselect_b64 s[14:15], -1, 0
	v_writelane_b32 v253, s14, 52
	s_cmp_eq_u32 s11, 6
	s_movk_i32 s55, 0x4000
	v_writelane_b32 v253, s15, 53
	s_cselect_b64 s[14:15], -1, 0
	v_writelane_b32 v253, s14, 54
	s_cmp_eq_u32 s11, 5
	s_mov_b32 s35, 0x3a800000
	v_writelane_b32 v253, s15, 55
	s_cselect_b64 s[14:15], -1, 0
	v_writelane_b32 v253, s14, 56
	s_cmp_eq_u32 s11, 4
	s_mov_b32 s19, 0xbfb8aa3b
	v_writelane_b32 v253, s15, 57
	s_cselect_b64 s[14:15], -1, 0
	v_writelane_b32 v253, s14, 58
	s_cmp_eq_u32 s11, 3
	s_mov_b32 s23, 0x40000
	v_writelane_b32 v253, s15, 59
	s_cselect_b64 s[14:15], -1, 0
	v_writelane_b32 v253, s14, 60
	s_cmp_eq_u32 s11, 2
	s_movk_i32 s86, 0x1600
	v_writelane_b32 v253, s15, 61
	s_cselect_b64 s[14:15], -1, 0
	v_writelane_b32 v253, s14, 62
	s_cmp_eq_u32 s11, 1
	s_movk_i32 s87, 0x4040
	v_writelane_b32 v253, s15, 63
	s_cselect_b64 s[14:15], -1, 0
	v_writelane_b32 v254, s14, 0
	s_cmp_eq_u32 s11, 0
	s_mov_b32 s88, 0
	s_mov_b32 s101, 0
	v_writelane_b32 v254, s15, 1
	s_cselect_b64 s[14:15], -1, 0
	s_lshl_b32 s11, s12, 2
	s_add_u32 s8, s8, s11
	v_writelane_b32 v254, s14, 2
	s_addc_u32 s9, s9, 0
	s_mov_b64 s[36:37], 0x20000
	v_writelane_b32 v254, s15, 3
	s_add_u32 s14, s8, 0x1400
	s_addc_u32 s15, s9, 0
	v_writelane_b32 v254, s14, 4
	s_add_u32 s8, s8, 0x2400
	s_addc_u32 s9, s9, 0
	v_writelane_b32 v254, s15, 5
	v_writelane_b32 v254, s8, 6
	s_mov_b64 s[62:63], 0x40000
	s_mov_b32 s25, -1
	v_writelane_b32 v254, s9, 7
	s_add_u32 s8, s0, 0x83400
	s_addc_u32 s9, s1, 0
	v_writelane_b32 v254, s8, 8
	s_add_u32 s0, s0, 0x83500
	s_addc_u32 s1, s1, 0
	v_writelane_b32 v254, s9, 9
	v_writelane_b32 v254, s0, 10
	v_readlane_b32 s8, v253, 2
	v_readlane_b32 s9, v253, 3
	v_writelane_b32 v254, s1, 11
	v_readlane_b32 s0, v253, 0
	v_readlane_b32 s1, v253, 1
	s_mul_i32 s0, s1, s0
	s_load_dword s1, s[8:9], 0xa0
	s_cmp_lt_i32 s6, 0
	s_mov_b64 s[30:31], 0x80
	s_mov_b64 s[16:17], 0x400
	s_mov_b64 s[40:41], 0x200
	s_waitcnt lgkmcnt(0)
;     __host__ __device__ bool next(int i, Unit& u) const {
;         if (rev_n) { i = rev_n - 1 - i; if (i < 0) return false; }
;         const long L = (long)i * G + c; if (L >= nwg) return false;
;         int wgid = (int)L; { const int q = nwg / NXCD, r = nwg % NXCD, xcd = wgid % NXCD, off = wgid / NXCD; wgid = (xcd < r ? xcd * (q + 1) : r * (q + 1) + (xcd - r) * q) + off; }
;         const int nig = WGM * nN, gid = wgid / nig, fm = gid * WGM, gsz = (nM % WGM == 0) ? WGM : ((nM - fm) < WGM ? (nM - fm) : WGM);
;         u.pm = fm + ((wgid % nig) % gsz); u.pn = (wgid % nig) / gsz; return true;
	s_mul_i32 s0, s0, s1
	v_writelane_b32 v254, s0, 12
	s_movk_i32 s0, 0x3ff
	v_and_or_b32 v0, v0, s0, v230
	s_mul_i32 s0, s6, 0x101
	s_cselect_b32 s0, s0, s7
	s_mul_i32 s1, s6, 0x81
	s_movk_i32 s7, 0x161
	s_cselect_b32 s1, s1, s10
	s_cselect_b32 s7, s7, 0x160
	s_add_i32 s0, s0, s5
	s_ashr_i32 s8, s0, 31
	s_lshr_b32 s8, s8, 25
	s_add_i32 s8, s0, s8
	s_and_b32 s9, s8, 0xff80
	s_sub_i32 s0, s0, s9
	s_bfe_i32 s9, s0, 0x80000
	s_bfe_u32 s9, s9, 0x3000c
	s_mul_i32 s6, s6, s7
	s_add_i32 s9, s0, s9
	s_add_i32 s6, s6, s5
	s_and_b32 s10, s9, 0xf8
	s_mul_hi_i32 s7, s6, 0x2e8ba2e9
	s_sub_i32 s0, s0, s10
	s_lshr_b32 s10, s7, 31
	s_ashr_i32 s7, s7, 5
	s_add_i32 s7, s7, s10
	s_mul_i32 s10, s7, 0xb0
	s_sub_i32 s6, s6, s10
	s_add_i32 s1, s1, s5
	s_bfe_u32 s10, s6, 0x3001c
	s_ashr_i32 s5, s1, 31
	s_add_i32 s10, s6, s10
	s_lshr_b32 s5, s5, 26
	s_and_b32 s11, s10, 0xfff8
	s_add_i32 s5, s1, s5
	s_sub_i32 s6, s6, s11
	s_and_b32 s11, s5, 0xffc0
	s_sub_i32 s1, s1, s11
	s_bfe_i32 s11, s1, 0x80000
	s_bfe_u32 s11, s11, 0x3000c
	s_add_i32 s11, s1, s11
	s_and_b32 s12, s11, 0xf8
	s_sub_i32 s12, s1, s12
	s_ashr_i32 s1, s8, 7
	s_lshl_b32 s1, s1, 3
	s_sext_i32_i8 s0, s0
	s_add_i32 s14, s1, s0
	s_lshl_b32 s0, s7, 3
	s_sext_i32_i16 s1, s10
	s_sext_i32_i16 s6, s6
	s_add_i32 s6, s0, s6
	s_ashr_i32 s0, s1, 3
	v_writelane_b32 v254, s0, 13
	s_lshr_b32 s0, s1, 3
	s_bfe_i64 s[0:1], s[0:1], 0x100000
	s_lshl_b64 s[0:1], s[0:1], 19
	v_writelane_b32 v254, s0, 14
	s_bfe_i32 s8, s9, 0x80000
	s_sext_i32_i16 s8, s8
	v_writelane_b32 v254, s1, 15
	s_ashr_i32 s0, s5, 6
	s_bfe_i32 s1, s11, 0x80000
	s_lshl_b32 s0, s0, 3
	s_sext_i32_i16 s5, s1
	s_sext_i32_i8 s1, s12
	s_add_i32 s10, s0, s1
	s_ashr_i32 s0, s8, 3
	v_writelane_b32 v254, s0, 16
	s_lshr_b32 s0, s8, 3
	s_bfe_i64 s[0:1], s[0:1], 0x100000
	s_lshl_b64 s[0:1], s[0:1], 19
	v_writelane_b32 v254, s0, 17
	s_ashr_i32 s7, s6, 31
	s_ashr_i32 s15, s14, 31
	v_writelane_b32 v254, s1, 18
	s_ashr_i32 s0, s5, 3
	v_writelane_b32 v254, s0, 19
	s_lshr_b32 s0, s5, 3
	s_bfe_i64 s[0:1], s[0:1], 0x100000
	s_lshl_b64 s[0:1], s[0:1], 19
	v_writelane_b32 v254, s0, 20
	s_ashr_i32 s11, s10, 31
	s_mov_b64 s[12:13], 0x60000
	v_writelane_b32 v254, s1, 21
	s_ashr_i32 s0, s4, 31
	v_writelane_b32 v254, s0, 22
	s_abs_i32 s0, s4
	v_writelane_b32 v254, s0, 23
	s_movk_i32 s0, 0x100
	v_cmp_gt_u32_e64 s[0:1], s0, v230
	s_mov_b32 s28, 0x3e6d3388
	s_mov_b32 s22, 0xbf38aa3b
	v_writelane_b32 v254, s0, 24
	s_mov_b32 s54, 0xbf3a00e3
	s_mov_b32 s66, 0x3f07dc22
	v_writelane_b32 v254, s1, 25
	s_lshl_b32 s0, s2, 5
	v_writelane_b32 v254, s0, 26
	s_lshl_b32 s0, s2, 12
	v_writelane_b32 v254, s0, 27
	s_add_i32 s0, 0, 0x17050
	v_writelane_b32 v254, s0, 28
	s_add_i32 s0, 0, 0x17060
	v_writelane_b32 v254, s0, 29
	s_add_i32 s0, 0, 0x17070
	v_writelane_b32 v254, s0, 30
	s_add_i32 s0, 0, 0x17080
	v_writelane_b32 v254, s0, 31
	s_add_i32 s0, 0, 0x17090
	v_writelane_b32 v254, s0, 32
	s_add_i32 s0, 0, 0x170a0
	v_writelane_b32 v254, s0, 33
	s_add_i32 s0, 0, 0x170b0
	v_writelane_b32 v254, s0, 34
	s_add_i32 s0, 0, 0x17180
	v_writelane_b32 v254, s0, 35
	s_add_i32 s0, 0, 0x20140
	v_writelane_b32 v254, s0, 36
	s_add_i32 s0, 0, 0x20144
	v_writelane_b32 v254, s0, 37
	v_cmp_eq_u32_e64 s[0:1], 0, v0
	s_mov_b32 s68, 0x3f35f0e3
	s_mov_b32 s26, 0xbe11a98e
	v_writelane_b32 v254, s0, 38
	s_mov_b32 s34, 0x3e027906
	v_writelane_b32 v197, s98, 4
	v_writelane_b32 v254, s1, 39
	s_mov_b32 s0, s6
	v_writelane_b32 v254, s0, 40
	v_writelane_b32 v197, s99, 5
	s_nop 0
	v_writelane_b32 v254, s1, 41
	s_lshl_b64 s[0:1], s[6:7], 19
	v_writelane_b32 v254, s0, 42
	s_nop 1
	v_writelane_b32 v254, s1, 43
	s_mov_b32 s0, s14
	v_writelane_b32 v254, s0, 44
	s_nop 1
	v_writelane_b32 v254, s1, 45
	s_lshl_b64 s[0:1], s[14:15], 19
	v_writelane_b32 v254, s0, 46
	s_nop 1
	v_writelane_b32 v254, s1, 47
	s_mov_b32 s0, s10
	v_writelane_b32 v254, s0, 48
	s_nop 1
	v_writelane_b32 v254, s1, 49
	s_lshl_b64 s[0:1], s[10:11], 19
	v_writelane_b32 v254, s0, 50
	s_nop 1
	v_writelane_b32 v254, s1, 51
	v_writelane_b32 v254, s60, 52
	s_nop 1
	v_writelane_b32 v254, s61, 53
	v_writelane_b32 v254, s64, 54
	s_nop 1
	v_writelane_b32 v254, s65, 55
	v_writelane_b32 v254, s70, 56
	s_nop 1
	v_writelane_b32 v254, s71, 57
	v_writelane_b32 v254, s72, 58
	s_nop 1
	v_writelane_b32 v254, s73, 59
	v_writelane_b32 v254, s74, 60
	s_nop 1
	v_writelane_b32 v254, s75, 61
	v_writelane_b32 v254, s76, 62
	s_nop 1
	v_writelane_b32 v254, s77, 63
	s_branch .LBB0_10

; __device__ __forceinline__ unsigned cvt_pk_bf16(float lo, float hi) { unsigned r; asm volatile("v_cvt_pk_bf16_f32 %0, %1, %2" : "=v"(r) : "v"(lo), "v"(hi)); return r; }
; #define PG8_STAGE(bufoff, gbase, voff) do { _Pragma("unroll") for (int _i = 0; _i < 2; ++_i) \
;         __builtin_amdgcn_global_load_lds((const unsigned*)((const char*)(gbase) + (voff)[_i]), (PG8_LAS unsigned*)(lds + (bufoff) + ldsw + _i * 8192), 16, 0, 0); } while (0)
; #define PG8_LDA(dst, b, h) do { _Pragma("unroll") for (int m = 0; m < 4; ++m) _Pragma("unroll") for (int k = 0; k < 2; ++k) dst[m][k] = *(const PG8_LAS bf16x8*)(lds + PG8_SA(b, h) + aoff + m * 2048 + k * 1024); } while (0)
;     __device__ __forceinline__ void operator()(const f32x4 (&acc)[2][2][4][2], const Unit& u, int wr, int wc, int fr, int fq, PG8_LAS unsigned char* lds, int& rs_pm, int& rs_tog) const {
;     ...
;                 const int row = row0 + ai * HALF + m * 16;
;                 const float rr = rt_[ai * HALF + m * 16], k1 = -kLog2e * rr, rr2 = rr * rr;
;                 const f32x4 a0 = acc[ai][0][m][0], a1 = acc[ai][0][m][1];
;                 f32x4 e0 = a0 * k1, e1 = a1 * k1;
;                 f32x4 g0 = (a0 * acc[ai][1][m][0]) * rr2, g1 = (a1 * acc[ai][1][m][1]) * rr2;
; #pragma unroll
;                 for (int i = 0; i < 4; ++i) { e0[i] = __builtin_amdgcn_exp2f(e0[i]); e1[i] = __builtin_amdgcn_exp2f(e1[i]); }
;                 e0 = e0 + 1.0f; e1 = e1 + 1.0f;
; #pragma unroll
;                 for (int i = 0; i < 4; ++i) { e0[i] = __builtin_amdgcn_rcpf(e0[i]); e1[i] = __builtin_amdgcn_rcpf(e1[i]); }
;                 g0 = g0 * e0; g1 = g1 * e1;
;                 const float b[8] = {g0[0], g0[1], g0[2], g0[3], g1[0], g1[1], g1[2], g1[3]};
;                 u32x4 w; w.x = cvt_pk_bf16(b[0], b[1]); w.y = cvt_pk_bf16(b[2], b[3]); w.z = cvt_pk_bf16(b[4], b[5]); w.w = cvt_pk_bf16(b[6], b[7]);
;                 *(u32x4*)(act + (size_t)row * ldc + col0) = w;
; template <class Epi, class Sched, bool ALIGN_EPI = false, bool SP2 = false>
; __device__ __forceinline__ void gemm_phase(PG8_LAS unsigned char* lds, const Gemm g, const Sched& S, const Epi& E) {
;     ...
;             PG8_LDB(B0, 0, 0); PG8_LDB(B1, 0, 1); PG8_SCHED; PG8_LDA(At, 0, 0); PG8_STAGE(PG8_SA(1, 1), a1 + hstep, voffA);
;             PG8_WAIT_V(8); PG8_WAIT_L(0); PG8_BAR; PG8_MMA(0, 0, At, B0); PG8_MMA(0, 1, At, B1); PG8_BAR; PG8_SCHED;
.LBB0_220:
	s_add_u32 s18, s60, 0xfffc0080
	s_addc_u32 s38, s61, -1
	s_add_i32 s39, 0, 0x10000
	s_cmp_eq_u32 s82, 12
	s_cselect_b32 s65, s47, s38
	s_cselect_b32 s64, s78, s18
	v_add_u32_e32 v145, s39, v141
	s_cselect_b32 s57, s49, s81
	s_cselect_b32 s56, s79, s80
	s_add_i32 s18, 0, 0x14000
	ds_read_b128 v[146:149], v145
	ds_read_b128 v[150:153], v145 offset:1024
	ds_read_b128 v[154:157], v145 offset:2048
	ds_read_b128 v[158:161], v145 offset:3072
	v_add_u32_e32 v145, s18, v141
	ds_read_b128 v[162:165], v145
	ds_read_b128 v[166:169], v145 offset:1024
	ds_read_b128 v[170:173], v145 offset:2048
	ds_read_b128 v[174:177], v145 offset:3072
	v_lshl_add_u64 v[194:195], s[60:61], 0, v[136:137]
	s_add_i32 m0, s29, 0xc000
	ds_read_b128 v[178:181], v144
	ds_read_b128 v[182:185], v144 offset:1024
	ds_read_b128 v[186:189], v144 offset:2048
	ds_read_b128 v[190:193], v144 offset:3072
	ds_read_b128 v[202:205], v144 offset:4096
	ds_read_b128 v[206:209], v144 offset:5120
	ds_read_b128 v[210:213], v144 offset:6144
	ds_read_b128 v[214:217], v144 offset:7168
	global_load_lds_dwordx4 v[194:195], off
	v_lshl_add_u64 v[194:195], s[60:61], 0, v[138:139]
	s_add_i32 m0, s29, 0xe000
	s_nop 0
	global_load_lds_dwordx4 v[194:195], off
	s_cmp_eq_u32 s101, 0
	s_cbranch_scc1 .Ldef_sp1_skip
	v_lshl_add_u32 v226, s73, 10, v142
	ds_read_b32 v227, v226
	ds_read_b32 v199, v226 offset:64
	ds_read_b32 v200, v226 offset:128
	ds_read_b32 v201, v226 offset:192
	s_lshl_b32 vcc_lo, s77, 8
	s_mul_i32 vcc_lo, vcc_lo, s86
	s_lshl_b32 vcc_hi, s100, 8
	s_add_i32 vcc_lo, vcc_lo, vcc_hi
	v_mul_u32_u24_e32 v198, 0x1600, v140
	v_lshl_add_u32 v198, v143, 1, v198
	v_add_u32_e32 v198, vcc_lo, v198
	s_waitcnt lgkmcnt(0)
	v_mul_f32_e32 v226, 0xbfb8aa3b, v227
	v_mul_f32_e32 v228, v227, v227
	v_pk_mul_f32 v[122:123], v[114:115], v[122:123]
	v_pk_mul_f32 v[124:125], v[116:117], v[124:125]
	v_pk_mul_f32 v[126:127], v[118:119], v[126:127]
	v_pk_mul_f32 v[128:129], v[120:121], v[128:129]
	v_pk_mul_f32 v[114:115], v[114:115], v[226:227] op_sel_hi:[1,0]
	v_pk_mul_f32 v[116:117], v[116:117], v[226:227] op_sel_hi:[1,0]
	v_pk_mul_f32 v[118:119], v[118:119], v[226:227] op_sel_hi:[1,0]
	v_pk_mul_f32 v[120:121], v[120:121], v[226:227] op_sel_hi:[1,0]
	v_exp_f32_e32 v114, v114
	v_exp_f32_e32 v115, v115
	v_exp_f32_e32 v116, v116
	v_exp_f32_e32 v117, v117
	v_exp_f32_e32 v118, v118
	v_exp_f32_e32 v119, v119
	v_exp_f32_e32 v120, v120
	v_exp_f32_e32 v121, v121
	v_pk_add_f32 v[114:115], v[114:115], 1.0 op_sel_hi:[1,0]
	v_pk_add_f32 v[116:117], v[116:117], 1.0 op_sel_hi:[1,0]
	v_pk_add_f32 v[118:119], v[118:119], 1.0 op_sel_hi:[1,0]
	v_pk_add_f32 v[120:121], v[120:121], 1.0 op_sel_hi:[1,0]
	v_rcp_f32_e32 v114, v114
	v_rcp_f32_e32 v115, v115
	v_rcp_f32_e32 v116, v116
	v_rcp_f32_e32 v117, v117
	v_rcp_f32_e32 v118, v118
	v_rcp_f32_e32 v119, v119
	v_rcp_f32_e32 v120, v120
	v_rcp_f32_e32 v121, v121
	v_pk_mul_f32 v[122:123], v[122:123], v[228:229] op_sel_hi:[1,0]
	v_pk_mul_f32 v[124:125], v[124:125], v[228:229] op_sel_hi:[1,0]
	v_pk_mul_f32 v[126:127], v[126:127], v[228:229] op_sel_hi:[1,0]
	v_pk_mul_f32 v[128:129], v[128:129], v[228:229] op_sel_hi:[1,0]
	v_pk_mul_f32 v[122:123], v[122:123], v[114:115]
	v_pk_mul_f32 v[124:125], v[124:125], v[116:117]
	v_pk_mul_f32 v[126:127], v[126:127], v[118:119]
	v_pk_mul_f32 v[128:129], v[128:129], v[120:121]
	v_cvt_pk_bf16_f32 v114, v122, v123
	v_cvt_pk_bf16_f32 v115, v124, v125
	v_cvt_pk_bf16_f32 v116, v126, v127
	v_cvt_pk_bf16_f32 v117, v128, v129
	global_store_dwordx4 v198, v[114:117], s[10:11]
	v_add_u32_e32 v198, 0x16000, v198
	v_mul_f32_e32 v226, 0xbfb8aa3b, v199
	v_mul_f32_e32 v228, v199, v199
	v_pk_mul_f32 v[106:107], v[98:99], v[106:107]
	v_pk_mul_f32 v[108:109], v[100:101], v[108:109]
	v_pk_mul_f32 v[110:111], v[102:103], v[110:111]
	v_pk_mul_f32 v[112:113], v[104:105], v[112:113]
	v_pk_mul_f32 v[98:99], v[98:99], v[226:227] op_sel_hi:[1,0]
	v_pk_mul_f32 v[100:101], v[100:101], v[226:227] op_sel_hi:[1,0]
	v_pk_mul_f32 v[102:103], v[102:103], v[226:227] op_sel_hi:[1,0]
	v_pk_mul_f32 v[104:105], v[104:105], v[226:227] op_sel_hi:[1,0]
	v_exp_f32_e32 v98, v98
	v_exp_f32_e32 v99, v99
	v_exp_f32_e32 v100, v100
	v_exp_f32_e32 v101, v101
	v_exp_f32_e32 v102, v102
	v_exp_f32_e32 v103, v103
	v_exp_f32_e32 v104, v104
	v_exp_f32_e32 v105, v105
	v_pk_add_f32 v[98:99], v[98:99], 1.0 op_sel_hi:[1,0]
	v_pk_add_f32 v[100:101], v[100:101], 1.0 op_sel_hi:[1,0]
	v_pk_add_f32 v[102:103], v[102:103], 1.0 op_sel_hi:[1,0]
	v_pk_add_f32 v[104:105], v[104:105], 1.0 op_sel_hi:[1,0]
	v_rcp_f32_e32 v98, v98
	v_rcp_f32_e32 v99, v99
	v_rcp_f32_e32 v100, v100
	v_rcp_f32_e32 v101, v101
	v_rcp_f32_e32 v102, v102
	v_rcp_f32_e32 v103, v103
	v_rcp_f32_e32 v104, v104
	v_rcp_f32_e32 v105, v105
	v_pk_mul_f32 v[106:107], v[106:107], v[228:229] op_sel_hi:[1,0]
	v_pk_mul_f32 v[108:109], v[108:109], v[228:229] op_sel_hi:[1,0]
	v_pk_mul_f32 v[110:111], v[110:111], v[228:229] op_sel_hi:[1,0]
	v_pk_mul_f32 v[112:113], v[112:113], v[228:229] op_sel_hi:[1,0]
	v_pk_mul_f32 v[106:107], v[106:107], v[98:99]
	v_pk_mul_f32 v[108:109], v[108:109], v[100:101]
	v_pk_mul_f32 v[110:111], v[110:111], v[102:103]
	v_pk_mul_f32 v[112:113], v[112:113], v[104:105]
	v_cvt_pk_bf16_f32 v98, v106, v107
	v_cvt_pk_bf16_f32 v99, v108, v109
	v_cvt_pk_bf16_f32 v100, v110, v111
	v_cvt_pk_bf16_f32 v101, v112, v113
	global_store_dwordx4 v198, v[98:101], s[10:11]
	v_add_u32_e32 v198, 0x16000, v198
	v_mul_f32_e32 v226, 0xbfb8aa3b, v200
	v_mul_f32_e32 v228, v200, v200
	v_pk_mul_f32 v[90:91], v[82:83], v[90:91]
	v_pk_mul_f32 v[92:93], v[84:85], v[92:93]
	v_pk_mul_f32 v[94:95], v[86:87], v[94:95]
	v_pk_mul_f32 v[96:97], v[88:89], v[96:97]
; __device__ __forceinline__ unsigned cvt_pk_bf16(float lo, float hi) { unsigned r; asm volatile("v_cvt_pk_bf16_f32 %0, %1, %2" : "=v"(r) : "v"(lo), "v"(hi)); return r; }
; #define PG8_MMA(ai, bj, At, Bt) do { __builtin_amdgcn_s_setprio(1); _Pragma("unroll") for (int m = 0; m < 4; ++m) _Pragma("unroll") for (int n = 0; n < 2; ++n) _Pragma("unroll") for (int k = 0; k < 2; ++k) \
;         acc[ai][bj][m][n] = __builtin_amdgcn_mfma_f32_16x16x32_bf16(Bt[n][k], At[m][k], acc[ai][bj][m][n], 0, 0, 0); __builtin_amdgcn_s_setprio(0); } while (0)
; #define PG8_WAIT_V(n) asm volatile("s_waitcnt vmcnt(" #n ")" ::: "memory")
; #define PG8_WAIT_L(n) asm volatile("s_waitcnt lgkmcnt(" #n ")" ::: "memory")
; #define PG8_BAR __builtin_amdgcn_s_barrier()
; #define PG8_SCHED __builtin_amdgcn_sched_barrier(0)
;     __device__ __forceinline__ void operator()(const f32x4 (&acc)[2][2][4][2], const Unit& u, int wr, int wc, int fr, int fq, PG8_LAS unsigned char* lds, int& rs_pm, int& rs_tog) const {
;     ...
;                 const int row = row0 + ai * HALF + m * 16;
;                 const float rr = rt_[ai * HALF + m * 16], k1 = -kLog2e * rr, rr2 = rr * rr;
;                 const f32x4 a0 = acc[ai][0][m][0], a1 = acc[ai][0][m][1];
;                 f32x4 e0 = a0 * k1, e1 = a1 * k1;
;                 f32x4 g0 = (a0 * acc[ai][1][m][0]) * rr2, g1 = (a1 * acc[ai][1][m][1]) * rr2;
; #pragma unroll
;                 for (int i = 0; i < 4; ++i) { e0[i] = __builtin_amdgcn_exp2f(e0[i]); e1[i] = __builtin_amdgcn_exp2f(e1[i]); }
;                 e0 = e0 + 1.0f; e1 = e1 + 1.0f;
; #pragma unroll
;                 for (int i = 0; i < 4; ++i) { e0[i] = __builtin_amdgcn_rcpf(e0[i]); e1[i] = __builtin_amdgcn_rcpf(e1[i]); }
;                 g0 = g0 * e0; g1 = g1 * e1;
;                 const float b[8] = {g0[0], g0[1], g0[2], g0[3], g1[0], g1[1], g1[2], g1[3]};
;                 u32x4 w; w.x = cvt_pk_bf16(b[0], b[1]); w.y = cvt_pk_bf16(b[2], b[3]); w.z = cvt_pk_bf16(b[4], b[5]); w.w = cvt_pk_bf16(b[6], b[7]);
;                 *(u32x4*)(act + (size_t)row * ldc + col0) = w;
; template <class Epi, class Sched, bool ALIGN_EPI = false, bool SP2 = false>
; __device__ __forceinline__ void gemm_phase(PG8_LAS unsigned char* lds, const Gemm g, const Sched& S, const Epi& E) {
;     ...
;             PG8_WAIT_V(8); PG8_WAIT_L(0); PG8_BAR; PG8_MMA(0, 0, At, B0); PG8_MMA(0, 1, At, B1); PG8_BAR; PG8_SCHED;
	v_pk_mul_f32 v[82:83], v[82:83], v[226:227] op_sel_hi:[1,0]
	v_pk_mul_f32 v[84:85], v[84:85], v[226:227] op_sel_hi:[1,0]
	v_pk_mul_f32 v[86:87], v[86:87], v[226:227] op_sel_hi:[1,0]
	v_pk_mul_f32 v[88:89], v[88:89], v[226:227] op_sel_hi:[1,0]
	v_exp_f32_e32 v82, v82
	v_exp_f32_e32 v83, v83
	v_exp_f32_e32 v84, v84
	v_exp_f32_e32 v85, v85
	v_exp_f32_e32 v86, v86
	v_exp_f32_e32 v87, v87
	v_exp_f32_e32 v88, v88
	v_exp_f32_e32 v89, v89
	v_pk_add_f32 v[82:83], v[82:83], 1.0 op_sel_hi:[1,0]
	v_pk_add_f32 v[84:85], v[84:85], 1.0 op_sel_hi:[1,0]
	v_pk_add_f32 v[86:87], v[86:87], 1.0 op_sel_hi:[1,0]
	v_pk_add_f32 v[88:89], v[88:89], 1.0 op_sel_hi:[1,0]
	v_rcp_f32_e32 v82, v82
	v_rcp_f32_e32 v83, v83
	v_rcp_f32_e32 v84, v84
	v_rcp_f32_e32 v85, v85
	v_rcp_f32_e32 v86, v86
	v_rcp_f32_e32 v87, v87
	v_rcp_f32_e32 v88, v88
	v_rcp_f32_e32 v89, v89
	v_pk_mul_f32 v[90:91], v[90:91], v[228:229] op_sel_hi:[1,0]
	v_pk_mul_f32 v[92:93], v[92:93], v[228:229] op_sel_hi:[1,0]
	v_pk_mul_f32 v[94:95], v[94:95], v[228:229] op_sel_hi:[1,0]
	v_pk_mul_f32 v[96:97], v[96:97], v[228:229] op_sel_hi:[1,0]
	v_pk_mul_f32 v[90:91], v[90:91], v[82:83]
	v_pk_mul_f32 v[92:93], v[92:93], v[84:85]
	v_pk_mul_f32 v[94:95], v[94:95], v[86:87]
	v_pk_mul_f32 v[96:97], v[96:97], v[88:89]
	v_cvt_pk_bf16_f32 v82, v90, v91
	v_cvt_pk_bf16_f32 v83, v92, v93
	v_cvt_pk_bf16_f32 v84, v94, v95
	v_cvt_pk_bf16_f32 v85, v96, v97
	global_store_dwordx4 v198, v[82:85], s[10:11]
	v_add_u32_e32 v198, 0x16000, v198
	v_mul_f32_e32 v226, 0xbfb8aa3b, v201
	v_mul_f32_e32 v228, v201, v201
	v_pk_mul_f32 v[74:75], v[66:67], v[74:75]
	v_pk_mul_f32 v[76:77], v[68:69], v[76:77]
	v_pk_mul_f32 v[78:79], v[70:71], v[78:79]
	v_pk_mul_f32 v[80:81], v[72:73], v[80:81]
	v_pk_mul_f32 v[66:67], v[66:67], v[226:227] op_sel_hi:[1,0]
	v_pk_mul_f32 v[68:69], v[68:69], v[226:227] op_sel_hi:[1,0]
	v_pk_mul_f32 v[70:71], v[70:71], v[226:227] op_sel_hi:[1,0]
	v_pk_mul_f32 v[72:73], v[72:73], v[226:227] op_sel_hi:[1,0]
	v_exp_f32_e32 v66, v66
	v_exp_f32_e32 v67, v67
	v_exp_f32_e32 v68, v68
	v_exp_f32_e32 v69, v69
	v_exp_f32_e32 v70, v70
	v_exp_f32_e32 v71, v71
	v_exp_f32_e32 v72, v72
	v_exp_f32_e32 v73, v73
	v_pk_add_f32 v[66:67], v[66:67], 1.0 op_sel_hi:[1,0]
	v_pk_add_f32 v[68:69], v[68:69], 1.0 op_sel_hi:[1,0]
	v_pk_add_f32 v[70:71], v[70:71], 1.0 op_sel_hi:[1,0]
	v_pk_add_f32 v[72:73], v[72:73], 1.0 op_sel_hi:[1,0]
	v_rcp_f32_e32 v66, v66
	v_rcp_f32_e32 v67, v67
	v_rcp_f32_e32 v68, v68
	v_rcp_f32_e32 v69, v69
	v_rcp_f32_e32 v70, v70
	v_rcp_f32_e32 v71, v71
	v_rcp_f32_e32 v72, v72
	v_rcp_f32_e32 v73, v73
	v_pk_mul_f32 v[74:75], v[74:75], v[228:229] op_sel_hi:[1,0]
	v_pk_mul_f32 v[76:77], v[76:77], v[228:229] op_sel_hi:[1,0]
	v_pk_mul_f32 v[78:79], v[78:79], v[228:229] op_sel_hi:[1,0]
	v_pk_mul_f32 v[80:81], v[80:81], v[228:229] op_sel_hi:[1,0]
	v_pk_mul_f32 v[74:75], v[74:75], v[66:67]
	v_pk_mul_f32 v[76:77], v[76:77], v[68:69]
	v_pk_mul_f32 v[78:79], v[78:79], v[70:71]
	v_pk_mul_f32 v[80:81], v[80:81], v[72:73]
	v_cvt_pk_bf16_f32 v66, v74, v75
	v_cvt_pk_bf16_f32 v67, v76, v77
	v_cvt_pk_bf16_f32 v68, v78, v79
	v_cvt_pk_bf16_f32 v69, v80, v81
	global_store_dwordx4 v198, v[66:69], s[10:11]
	s_nop 1
	v_mov_b64_e32 v[114:115], 0
	v_mov_b64_e32 v[116:117], 0
	v_mov_b64_e32 v[118:119], 0
	v_mov_b64_e32 v[120:121], 0
	v_mov_b64_e32 v[122:123], 0
	v_mov_b64_e32 v[124:125], 0
	v_mov_b64_e32 v[126:127], 0
	v_mov_b64_e32 v[128:129], 0
	v_mov_b64_e32 v[98:99], 0
	v_mov_b64_e32 v[100:101], 0
	v_mov_b64_e32 v[102:103], 0
	v_mov_b64_e32 v[104:105], 0
	v_mov_b64_e32 v[106:107], 0
	v_mov_b64_e32 v[108:109], 0
	v_mov_b64_e32 v[110:111], 0
	v_mov_b64_e32 v[112:113], 0
	v_mov_b64_e32 v[82:83], 0
	v_mov_b64_e32 v[84:85], 0
	v_mov_b64_e32 v[86:87], 0
	v_mov_b64_e32 v[88:89], 0
	v_mov_b64_e32 v[90:91], 0
	v_mov_b64_e32 v[92:93], 0
	v_mov_b64_e32 v[94:95], 0
	v_mov_b64_e32 v[96:97], 0
	v_mov_b64_e32 v[66:67], 0
	v_mov_b64_e32 v[68:69], 0
	v_mov_b64_e32 v[70:71], 0
	v_mov_b64_e32 v[72:73], 0
	v_mov_b64_e32 v[74:75], 0
	v_mov_b64_e32 v[76:77], 0
	v_mov_b64_e32 v[78:79], 0
	v_mov_b64_e32 v[80:81], 0
	s_waitcnt vmcnt(12)
	s_branch .Ldef_sp1_join
.Ldef_sp1_skip:
	s_waitcnt vmcnt(8)
.Ldef_sp1_join:
	s_waitcnt lgkmcnt(0)
	s_barrier
	s_setprio 1
	s_waitcnt lgkmcnt(0)
	v_mfma_f32_16x16x32_bf16 v[114:117], v[146:149], v[178:181], v[114:117]
	v_mfma_f32_16x16x32_bf16 v[118:121], v[154:157], v[178:181], v[118:121]
	v_mfma_f32_16x16x32_bf16 v[98:101], v[146:149], v[186:189], v[98:101]
	v_mfma_f32_16x16x32_bf16 v[102:105], v[154:157], v[186:189], v[102:105]
	v_mfma_f32_16x16x32_bf16 v[82:85], v[146:149], v[202:205], v[82:85]
	v_mfma_f32_16x16x32_bf16 v[86:89], v[154:157], v[202:205], v[86:89]
	v_mfma_f32_16x16x32_bf16 v[66:69], v[146:149], v[210:213], v[66:69]
	v_mfma_f32_16x16x32_bf16 v[70:73], v[154:157], v[210:213], v[70:73]
	v_mfma_f32_16x16x32_bf16 v[114:117], v[150:153], v[182:185], v[114:117]
	v_mfma_f32_16x16x32_bf16 v[118:121], v[158:161], v[182:185], v[118:121]
	v_mfma_f32_16x16x32_bf16 v[98:101], v[150:153], v[190:193], v[98:101]
	v_mfma_f32_16x16x32_bf16 v[102:105], v[158:161], v[190:193], v[102:105]
	v_mfma_f32_16x16x32_bf16 v[82:85], v[150:153], v[206:209], v[82:85]
	v_mfma_f32_16x16x32_bf16 v[86:89], v[158:161], v[206:209], v[86:89]
	v_mfma_f32_16x16x32_bf16 v[66:69], v[150:153], v[214:217], v[66:69]
	v_mfma_f32_16x16x32_bf16 v[70:73], v[158:161], v[214:217], v[70:73]
	s_setprio 0
	s_setprio 1
	v_mfma_f32_16x16x32_bf16 v[122:125], v[162:165], v[178:181], v[122:125]
	v_mfma_f32_16x16x32_bf16 v[126:129], v[170:173], v[178:181], v[126:129]
	v_mfma_f32_16x16x32_bf16 v[106:109], v[162:165], v[186:189], v[106:109]
	v_mfma_f32_16x16x32_bf16 v[110:113], v[170:173], v[186:189], v[110:113]
	v_mfma_f32_16x16x32_bf16 v[90:93], v[162:165], v[202:205], v[90:93]
	v_mfma_f32_16x16x32_bf16 v[94:97], v[170:173], v[202:205], v[94:97]
	v_mfma_f32_16x16x32_bf16 v[74:77], v[162:165], v[210:213], v[74:77]
	v_mfma_f32_16x16x32_bf16 v[78:81], v[170:173], v[210:213], v[78:81]
	v_mfma_f32_16x16x32_bf16 v[122:125], v[166:169], v[182:185], v[122:125]
	v_mfma_f32_16x16x32_bf16 v[126:129], v[174:177], v[182:185], v[126:129]
	v_mfma_f32_16x16x32_bf16 v[106:109], v[166:169], v[190:193], v[106:109]
	v_mfma_f32_16x16x32_bf16 v[110:113], v[174:177], v[190:193], v[110:113]
	v_mfma_f32_16x16x32_bf16 v[90:93], v[166:169], v[206:209], v[90:93]
	v_mfma_f32_16x16x32_bf16 v[94:97], v[174:177], v[206:209], v[94:97]
	v_mfma_f32_16x16x32_bf16 v[74:77], v[166:169], v[214:217], v[74:77]
	v_mfma_f32_16x16x32_bf16 v[78:81], v[174:177], v[214:217], v[78:81]
	s_setprio 0
	s_barrier
; __device__ __forceinline__ unsigned cvt_pk_bf16(float lo, float hi) { unsigned r; asm volatile("v_cvt_pk_bf16_f32 %0, %1, %2" : "=v"(r) : "v"(lo), "v"(hi)); return r; }
; #define PG8_STAGE(bufoff, gbase, voff) do { _Pragma("unroll") for (int _i = 0; _i < 2; ++_i) \
;         __builtin_amdgcn_global_load_lds((const unsigned*)((const char*)(gbase) + (voff)[_i]), (PG8_LAS unsigned*)(lds + (bufoff) + ldsw + _i * 8192), 16, 0, 0); } while (0)
; #define PG8_LDA(dst, b, h) do { _Pragma("unroll") for (int m = 0; m < 4; ++m) _Pragma("unroll") for (int k = 0; k < 2; ++k) dst[m][k] = *(const PG8_LAS bf16x8*)(lds + PG8_SA(b, h) + aoff + m * 2048 + k * 1024); } while (0)
;     __device__ __forceinline__ void operator()(const f32x4 (&acc)[2][2][4][2], const Unit& u, int wr, int wc, int fr, int fq, PG8_LAS unsigned char* lds, int& rs_pm, int& rs_tog) const {
;     ...
;                 const int row = row0 + ai * HALF + m * 16;
;                 const float rr = rt_[ai * HALF + m * 16], k1 = -kLog2e * rr, rr2 = rr * rr;
;                 const f32x4 a0 = acc[ai][0][m][0], a1 = acc[ai][0][m][1];
;                 f32x4 e0 = a0 * k1, e1 = a1 * k1;
;                 f32x4 g0 = (a0 * acc[ai][1][m][0]) * rr2, g1 = (a1 * acc[ai][1][m][1]) * rr2;
; #pragma unroll
;                 for (int i = 0; i < 4; ++i) { e0[i] = __builtin_amdgcn_exp2f(e0[i]); e1[i] = __builtin_amdgcn_exp2f(e1[i]); }
;                 e0 = e0 + 1.0f; e1 = e1 + 1.0f;
; #pragma unroll
;                 for (int i = 0; i < 4; ++i) { e0[i] = __builtin_amdgcn_rcpf(e0[i]); e1[i] = __builtin_amdgcn_rcpf(e1[i]); }
;                 g0 = g0 * e0; g1 = g1 * e1;
;                 const float b[8] = {g0[0], g0[1], g0[2], g0[3], g1[0], g1[1], g1[2], g1[3]};
;                 u32x4 w; w.x = cvt_pk_bf16(b[0], b[1]); w.y = cvt_pk_bf16(b[2], b[3]); w.z = cvt_pk_bf16(b[4], b[5]); w.w = cvt_pk_bf16(b[6], b[7]);
;                 *(u32x4*)(act + (size_t)row * ldc + col0) = w;
; template <class Epi, class Sched, bool ALIGN_EPI = false, bool SP2 = false>
; __device__ __forceinline__ void gemm_phase(PG8_LAS unsigned char* lds, const Gemm g, const Sched& S, const Epi& E) {
;     ...
;             PG8_LDA(At, 0, 1); PG8_STAGE(PG8_SB(0, 0), b2, voffB); PG8_STAGE(PG8_SB(0, 1), b2 + hstep, voffB); PG8_STAGE(PG8_SA(0, 0), a2, voffA);
	s_add_i32 s38, s39, s27
	v_lshl_add_u64 v[194:195], s[56:57], 0, v[0:1]
	s_mov_b32 m0, s38
	ds_read_b128 v[178:181], v144 offset:16384
	ds_read_b128 v[182:185], v144 offset:17408
	ds_read_b128 v[186:189], v144 offset:18432
	ds_read_b128 v[190:193], v144 offset:19456
	ds_read_b128 v[202:205], v144 offset:20480
	ds_read_b128 v[206:209], v144 offset:21504
	ds_read_b128 v[210:213], v144 offset:22528
	ds_read_b128 v[214:217], v144 offset:23552
	global_load_lds_dwordx4 v[194:195], off
	s_add_i32 m0, s38, 0x2000
	s_add_u32 s38, s56, 0x40000
	v_lshl_add_u64 v[218:219], s[56:57], 0, v[130:131]
	s_addc_u32 s39, s57, 0
	s_add_i32 s18, s18, s27
	global_load_lds_dwordx4 v[218:219], off
	v_lshl_add_u64 v[220:221], s[38:39], 0, v[0:1]
	s_mov_b32 m0, s18
	v_lshl_add_u64 v[222:223], s[64:65], 0, v[132:133]
	global_load_lds_dwordx4 v[220:221], off
	v_lshl_add_u64 v[220:221], s[38:39], 0, v[130:131]
	s_add_i32 m0, s18, 0x2000
	s_nop 0
	global_load_lds_dwordx4 v[220:221], off
	v_lshl_add_u64 v[220:221], s[64:65], 0, v[134:135]
	s_mov_b32 m0, s29
	s_nop 0
	global_load_lds_dwordx4 v[220:221], off
	s_mov_b32 m0, s33
	s_nop 0
	global_load_lds_dwordx4 v[222:223], off
	s_cmp_eq_u32 s101, 0
	s_cbranch_scc1 .Ldef_sp2_skip
	v_lshl_add_u32 v226, s73, 10, v142
	ds_read_b32 v227, v226 offset:512
	ds_read_b32 v199, v226 offset:576
	ds_read_b32 v200, v226 offset:640
	ds_read_b32 v201, v226 offset:704
	s_lshl_b32 vcc_lo, s77, 8
	s_addk_i32 vcc_lo, 0x80
	s_mul_i32 vcc_lo, vcc_lo, s86
	s_lshl_b32 vcc_hi, s100, 8
	s_add_i32 vcc_lo, vcc_lo, vcc_hi
	v_mul_u32_u24_e32 v198, 0x1600, v140
	v_lshl_add_u32 v198, v143, 1, v198
	v_add_u32_e32 v198, vcc_lo, v198
	s_waitcnt lgkmcnt(0)
	v_mul_f32_e32 v226, 0xbfb8aa3b, v227
	v_mul_f32_e32 v228, v227, v227
	v_pk_mul_f32 v[58:59], v[50:51], v[58:59]
	v_pk_mul_f32 v[60:61], v[52:53], v[60:61]
	v_pk_mul_f32 v[62:63], v[54:55], v[62:63]
	v_pk_mul_f32 v[64:65], v[56:57], v[64:65]
	v_pk_mul_f32 v[50:51], v[50:51], v[226:227] op_sel_hi:[1,0]
	v_pk_mul_f32 v[52:53], v[52:53], v[226:227] op_sel_hi:[1,0]
	v_pk_mul_f32 v[54:55], v[54:55], v[226:227] op_sel_hi:[1,0]
	v_pk_mul_f32 v[56:57], v[56:57], v[226:227] op_sel_hi:[1,0]
	v_exp_f32_e32 v50, v50
	v_exp_f32_e32 v51, v51
	v_exp_f32_e32 v52, v52
	v_exp_f32_e32 v53, v53
	v_exp_f32_e32 v54, v54
	v_exp_f32_e32 v55, v55
	v_exp_f32_e32 v56, v56
	v_exp_f32_e32 v57, v57
	v_pk_add_f32 v[50:51], v[50:51], 1.0 op_sel_hi:[1,0]
	v_pk_add_f32 v[52:53], v[52:53], 1.0 op_sel_hi:[1,0]
	v_pk_add_f32 v[54:55], v[54:55], 1.0 op_sel_hi:[1,0]
	v_pk_add_f32 v[56:57], v[56:57], 1.0 op_sel_hi:[1,0]
	v_rcp_f32_e32 v50, v50
	v_rcp_f32_e32 v51, v51
	v_rcp_f32_e32 v52, v52
	v_rcp_f32_e32 v53, v53
	v_rcp_f32_e32 v54, v54
	v_rcp_f32_e32 v55, v55
	v_rcp_f32_e32 v56, v56
	v_rcp_f32_e32 v57, v57
	v_pk_mul_f32 v[58:59], v[58:59], v[228:229] op_sel_hi:[1,0]
	v_pk_mul_f32 v[60:61], v[60:61], v[228:229] op_sel_hi:[1,0]
	v_pk_mul_f32 v[62:63], v[62:63], v[228:229] op_sel_hi:[1,0]
	v_pk_mul_f32 v[64:65], v[64:65], v[228:229] op_sel_hi:[1,0]
	v_pk_mul_f32 v[58:59], v[58:59], v[50:51]
	v_pk_mul_f32 v[60:61], v[60:61], v[52:53]
	v_pk_mul_f32 v[62:63], v[62:63], v[54:55]
	v_pk_mul_f32 v[64:65], v[64:65], v[56:57]
	v_cvt_pk_bf16_f32 v50, v58, v59
	v_cvt_pk_bf16_f32 v51, v60, v61
	v_cvt_pk_bf16_f32 v52, v62, v63
	v_cvt_pk_bf16_f32 v53, v64, v65
	global_store_dwordx4 v198, v[50:53], s[10:11]
	v_add_u32_e32 v198, 0x16000, v198
	v_mul_f32_e32 v226, 0xbfb8aa3b, v199
	v_mul_f32_e32 v228, v199, v199
	v_pk_mul_f32 v[42:43], v[34:35], v[42:43]
	v_pk_mul_f32 v[44:45], v[36:37], v[44:45]
	v_pk_mul_f32 v[46:47], v[38:39], v[46:47]
	v_pk_mul_f32 v[48:49], v[40:41], v[48:49]
	v_pk_mul_f32 v[34:35], v[34:35], v[226:227] op_sel_hi:[1,0]
	v_pk_mul_f32 v[36:37], v[36:37], v[226:227] op_sel_hi:[1,0]
	v_pk_mul_f32 v[38:39], v[38:39], v[226:227] op_sel_hi:[1,0]
	v_pk_mul_f32 v[40:41], v[40:41], v[226:227] op_sel_hi:[1,0]
	v_exp_f32_e32 v34, v34
	v_exp_f32_e32 v35, v35
	v_exp_f32_e32 v36, v36
	v_exp_f32_e32 v37, v37
	v_exp_f32_e32 v38, v38
	v_exp_f32_e32 v39, v39
	v_exp_f32_e32 v40, v40
	v_exp_f32_e32 v41, v41
	v_pk_add_f32 v[34:35], v[34:35], 1.0 op_sel_hi:[1,0]
	v_pk_add_f32 v[36:37], v[36:37], 1.0 op_sel_hi:[1,0]
	v_pk_add_f32 v[38:39], v[38:39], 1.0 op_sel_hi:[1,0]
	v_pk_add_f32 v[40:41], v[40:41], 1.0 op_sel_hi:[1,0]
	v_rcp_f32_e32 v34, v34
	v_rcp_f32_e32 v35, v35
	v_rcp_f32_e32 v36, v36
	v_rcp_f32_e32 v37, v37
	v_rcp_f32_e32 v38, v38
	v_rcp_f32_e32 v39, v39
	v_rcp_f32_e32 v40, v40
	v_rcp_f32_e32 v41, v41
	v_pk_mul_f32 v[42:43], v[42:43], v[228:229] op_sel_hi:[1,0]
	v_pk_mul_f32 v[44:45], v[44:45], v[228:229] op_sel_hi:[1,0]
	v_pk_mul_f32 v[46:47], v[46:47], v[228:229] op_sel_hi:[1,0]
; __device__ __forceinline__ unsigned cvt_pk_bf16(float lo, float hi) { unsigned r; asm volatile("v_cvt_pk_bf16_f32 %0, %1, %2" : "=v"(r) : "v"(lo), "v"(hi)); return r; }
;     __device__ __forceinline__ void operator()(const f32x4 (&acc)[2][2][4][2], const Unit& u, int wr, int wc, int fr, int fq, PG8_LAS unsigned char* lds, int& rs_pm, int& rs_tog) const {
;     ...
;                 const int row = row0 + ai * HALF + m * 16;
;                 const float rr = rt_[ai * HALF + m * 16], k1 = -kLog2e * rr, rr2 = rr * rr;
;                 const f32x4 a0 = acc[ai][0][m][0], a1 = acc[ai][0][m][1];
;                 f32x4 e0 = a0 * k1, e1 = a1 * k1;
;                 f32x4 g0 = (a0 * acc[ai][1][m][0]) * rr2, g1 = (a1 * acc[ai][1][m][1]) * rr2;
; #pragma unroll
;                 for (int i = 0; i < 4; ++i) { e0[i] = __builtin_amdgcn_exp2f(e0[i]); e1[i] = __builtin_amdgcn_exp2f(e1[i]); }
;                 e0 = e0 + 1.0f; e1 = e1 + 1.0f;
; #pragma unroll
;                 for (int i = 0; i < 4; ++i) { e0[i] = __builtin_amdgcn_rcpf(e0[i]); e1[i] = __builtin_amdgcn_rcpf(e1[i]); }
;                 g0 = g0 * e0; g1 = g1 * e1;
;                 const float b[8] = {g0[0], g0[1], g0[2], g0[3], g1[0], g1[1], g1[2], g1[3]};
;                 u32x4 w; w.x = cvt_pk_bf16(b[0], b[1]); w.y = cvt_pk_bf16(b[2], b[3]); w.z = cvt_pk_bf16(b[4], b[5]); w.w = cvt_pk_bf16(b[6], b[7]);
;                 *(u32x4*)(act + (size_t)row * ldc + col0) = w;
; template <class Epi, class Sched, bool ALIGN_EPI = false, bool SP2 = false>
; __device__ __forceinline__ void gemm_phase(PG8_LAS unsigned char* lds, const Gemm g, const Sched& S, const Epi& E) {
;     ...
;         for (int a = 0; a < 2; ++a)
; #pragma unroll
;             for (int b = 0; b < 2; ++b)
; #pragma unroll
;                 for (int m = 0; m < 4; ++m)
; #pragma unroll
;                     for (int n = 0; n < 2; ++n) { unsigned long long lo_, hi_; asm volatile("v_mov_b64 %0, 0\n\tv_mov_b64 %1, 0" : "=v"(lo_), "=v"(hi_)); acc[a][b][m][n] = __builtin_bit_cast(f32x4, (u64x2_t){lo_, hi_}); }
	v_pk_mul_f32 v[48:49], v[48:49], v[228:229] op_sel_hi:[1,0]
	v_pk_mul_f32 v[42:43], v[42:43], v[34:35]
	v_pk_mul_f32 v[44:45], v[44:45], v[36:37]
	v_pk_mul_f32 v[46:47], v[46:47], v[38:39]
	v_pk_mul_f32 v[48:49], v[48:49], v[40:41]
	v_cvt_pk_bf16_f32 v34, v42, v43
	v_cvt_pk_bf16_f32 v35, v44, v45
	v_cvt_pk_bf16_f32 v36, v46, v47
	v_cvt_pk_bf16_f32 v37, v48, v49
	global_store_dwordx4 v198, v[34:37], s[10:11]
	v_add_u32_e32 v198, 0x16000, v198
	v_mul_f32_e32 v226, 0xbfb8aa3b, v200
	v_mul_f32_e32 v228, v200, v200
	v_pk_mul_f32 v[26:27], v[18:19], v[26:27]
	v_pk_mul_f32 v[28:29], v[20:21], v[28:29]
	v_pk_mul_f32 v[30:31], v[22:23], v[30:31]
	v_pk_mul_f32 v[32:33], v[24:25], v[32:33]
	v_pk_mul_f32 v[18:19], v[18:19], v[226:227] op_sel_hi:[1,0]
	v_pk_mul_f32 v[20:21], v[20:21], v[226:227] op_sel_hi:[1,0]
	v_pk_mul_f32 v[22:23], v[22:23], v[226:227] op_sel_hi:[1,0]
	v_pk_mul_f32 v[24:25], v[24:25], v[226:227] op_sel_hi:[1,0]
	v_exp_f32_e32 v18, v18
	v_exp_f32_e32 v19, v19
	v_exp_f32_e32 v20, v20
	v_exp_f32_e32 v21, v21
	v_exp_f32_e32 v22, v22
	v_exp_f32_e32 v23, v23
	v_exp_f32_e32 v24, v24
	v_exp_f32_e32 v25, v25
	v_pk_add_f32 v[18:19], v[18:19], 1.0 op_sel_hi:[1,0]
	v_pk_add_f32 v[20:21], v[20:21], 1.0 op_sel_hi:[1,0]
	v_pk_add_f32 v[22:23], v[22:23], 1.0 op_sel_hi:[1,0]
	v_pk_add_f32 v[24:25], v[24:25], 1.0 op_sel_hi:[1,0]
	v_rcp_f32_e32 v18, v18
	v_rcp_f32_e32 v19, v19
	v_rcp_f32_e32 v20, v20
	v_rcp_f32_e32 v21, v21
	v_rcp_f32_e32 v22, v22
	v_rcp_f32_e32 v23, v23
	v_rcp_f32_e32 v24, v24
	v_rcp_f32_e32 v25, v25
	v_pk_mul_f32 v[26:27], v[26:27], v[228:229] op_sel_hi:[1,0]
	v_pk_mul_f32 v[28:29], v[28:29], v[228:229] op_sel_hi:[1,0]
	v_pk_mul_f32 v[30:31], v[30:31], v[228:229] op_sel_hi:[1,0]
	v_pk_mul_f32 v[32:33], v[32:33], v[228:229] op_sel_hi:[1,0]
	v_pk_mul_f32 v[26:27], v[26:27], v[18:19]
	v_pk_mul_f32 v[28:29], v[28:29], v[20:21]
	v_pk_mul_f32 v[30:31], v[30:31], v[22:23]
	v_pk_mul_f32 v[32:33], v[32:33], v[24:25]
	v_cvt_pk_bf16_f32 v18, v26, v27
	v_cvt_pk_bf16_f32 v19, v28, v29
	v_cvt_pk_bf16_f32 v20, v30, v31
	v_cvt_pk_bf16_f32 v21, v32, v33
	global_store_dwordx4 v198, v[18:21], s[10:11]
	v_add_u32_e32 v198, 0x16000, v198
	v_mul_f32_e32 v226, 0xbfb8aa3b, v201
	v_mul_f32_e32 v228, v201, v201
	v_pk_mul_f32 v[10:11], v[2:3], v[10:11]
	v_pk_mul_f32 v[12:13], v[4:5], v[12:13]
	v_pk_mul_f32 v[14:15], v[6:7], v[14:15]
	v_pk_mul_f32 v[16:17], v[8:9], v[16:17]
	v_pk_mul_f32 v[2:3], v[2:3], v[226:227] op_sel_hi:[1,0]
	v_pk_mul_f32 v[4:5], v[4:5], v[226:227] op_sel_hi:[1,0]
	v_pk_mul_f32 v[6:7], v[6:7], v[226:227] op_sel_hi:[1,0]
	v_pk_mul_f32 v[8:9], v[8:9], v[226:227] op_sel_hi:[1,0]
	v_exp_f32_e32 v2, v2
	v_exp_f32_e32 v3, v3
	v_exp_f32_e32 v4, v4
	v_exp_f32_e32 v5, v5
	v_exp_f32_e32 v6, v6
	v_exp_f32_e32 v7, v7
	v_exp_f32_e32 v8, v8
	v_exp_f32_e32 v9, v9
	v_pk_add_f32 v[2:3], v[2:3], 1.0 op_sel_hi:[1,0]
	v_pk_add_f32 v[4:5], v[4:5], 1.0 op_sel_hi:[1,0]
	v_pk_add_f32 v[6:7], v[6:7], 1.0 op_sel_hi:[1,0]
	v_pk_add_f32 v[8:9], v[8:9], 1.0 op_sel_hi:[1,0]
	v_rcp_f32_e32 v2, v2
	v_rcp_f32_e32 v3, v3
	v_rcp_f32_e32 v4, v4
	v_rcp_f32_e32 v5, v5
	v_rcp_f32_e32 v6, v6
	v_rcp_f32_e32 v7, v7
	v_rcp_f32_e32 v8, v8
	v_rcp_f32_e32 v9, v9
	v_pk_mul_f32 v[10:11], v[10:11], v[228:229] op_sel_hi:[1,0]
	v_pk_mul_f32 v[12:13], v[12:13], v[228:229] op_sel_hi:[1,0]
	v_pk_mul_f32 v[14:15], v[14:15], v[228:229] op_sel_hi:[1,0]
	v_pk_mul_f32 v[16:17], v[16:17], v[228:229] op_sel_hi:[1,0]
	v_pk_mul_f32 v[10:11], v[10:11], v[2:3]
	v_pk_mul_f32 v[12:13], v[12:13], v[4:5]
	v_pk_mul_f32 v[14:15], v[14:15], v[6:7]
	v_pk_mul_f32 v[16:17], v[16:17], v[8:9]
	v_cvt_pk_bf16_f32 v2, v10, v11
	v_cvt_pk_bf16_f32 v3, v12, v13
	v_cvt_pk_bf16_f32 v4, v14, v15
	v_cvt_pk_bf16_f32 v5, v16, v17
	global_store_dwordx4 v198, v[2:5], s[10:11]
	s_nop 1
	v_mov_b64_e32 v[50:51], 0
	v_mov_b64_e32 v[52:53], 0
	v_mov_b64_e32 v[54:55], 0
	v_mov_b64_e32 v[56:57], 0
	v_mov_b64_e32 v[58:59], 0
	v_mov_b64_e32 v[60:61], 0
	v_mov_b64_e32 v[62:63], 0
	v_mov_b64_e32 v[64:65], 0
	v_mov_b64_e32 v[34:35], 0
	v_mov_b64_e32 v[36:37], 0
	v_mov_b64_e32 v[38:39], 0
	v_mov_b64_e32 v[40:41], 0
	v_mov_b64_e32 v[42:43], 0
	v_mov_b64_e32 v[44:45], 0
	v_mov_b64_e32 v[46:47], 0
	v_mov_b64_e32 v[48:49], 0
	v_mov_b64_e32 v[18:19], 0
	v_mov_b64_e32 v[20:21], 0
	v_mov_b64_e32 v[22:23], 0
	v_mov_b64_e32 v[24:25], 0
	v_mov_b64_e32 v[26:27], 0
	v_mov_b64_e32 v[28:29], 0
	v_mov_b64_e32 v[30:31], 0
	v_mov_b64_e32 v[32:33], 0
	v_mov_b64_e32 v[2:3], 0
	v_mov_b64_e32 v[4:5], 0
	v_mov_b64_e32 v[6:7], 0
	v_mov_b64_e32 v[8:9], 0
	v_mov_b64_e32 v[10:11], 0
	v_mov_b64_e32 v[12:13], 0
	v_mov_b64_e32 v[14:15], 0
	v_mov_b64_e32 v[16:17], 0
	s_mov_b32 s101, 0
	s_waitcnt vmcnt(16)
	s_branch .Ldef_sp2_join

; #define PG8_STAGE(bufoff, gbase, voff) do { _Pragma("unroll") for (int _i = 0; _i < 2; ++_i) \
;         __builtin_amdgcn_global_load_lds((const unsigned*)((const char*)(gbase) + (voff)[_i]), (PG8_LAS unsigned*)(lds + (bufoff) + ldsw + _i * 8192), 16, 0, 0); } while (0)
; #define PG8_LDA(dst, b, h) do { _Pragma("unroll") for (int m = 0; m < 4; ++m) _Pragma("unroll") for (int k = 0; k < 2; ++k) dst[m][k] = *(const PG8_LAS bf16x8*)(lds + PG8_SA(b, h) + aoff + m * 2048 + k * 1024); } while (0)
; #define PG8_LDB(dst, b, h) do { _Pragma("unroll") for (int n = 0; n < 2; ++n) _Pragma("unroll") for (int k = 0; k < 2; ++k) dst[n][k] = *(const PG8_LAS bf16x8*)(lds + PG8_SB(b, h) + boff + n * 2048 + k * 1024); } while (0)
; #define PG8_MMA(ai, bj, At, Bt) do { __builtin_amdgcn_s_setprio(1); _Pragma("unroll") for (int m = 0; m < 4; ++m) _Pragma("unroll") for (int n = 0; n < 2; ++n) _Pragma("unroll") for (int k = 0; k < 2; ++k) \
;         acc[ai][bj][m][n] = __builtin_amdgcn_mfma_f32_16x16x32_bf16(Bt[n][k], At[m][k], acc[ai][bj][m][n], 0, 0, 0); __builtin_amdgcn_s_setprio(0); } while (0)
; #define PG8_WAIT_V(n) asm volatile("s_waitcnt vmcnt(" #n ")" ::: "memory")
; #define PG8_WAIT_L(n) asm volatile("s_waitcnt lgkmcnt(" #n ")" ::: "memory")
; #define PG8_BAR __builtin_amdgcn_s_barrier()
; #define PG8_SCHED __builtin_amdgcn_sched_barrier(0)
; template <class Epi, class Sched, bool ALIGN_EPI = false, bool SP2 = false>
; __device__ __forceinline__ void gemm_phase(PG8_LAS unsigned char* lds, const Gemm g, const Sched& S, const Epi& E) {
;     ...
;             PG8_WAIT_V(8); PG8_WAIT_L(0); PG8_BAR; PG8_MMA(1, 0, At, B0); PG8_MMA(1, 1, At, B1); PG8_BAR; PG8_SCHED;
;             PG8_LDB(B0, 1, 0); PG8_LDB(B1, 1, 1); PG8_SCHED; PG8_LDA(At, 1, 0); PG8_STAGE(PG8_SA(0, 1), a2 + hstep, voffA);
;             PG8_WAIT_V(8); PG8_WAIT_L(0); PG8_BAR; PG8_MMA(0, 0, At, B0); PG8_MMA(0, 1, At, B1); PG8_BAR; PG8_SCHED;
.Ldef_sp2_join:
	s_waitcnt lgkmcnt(0)
	s_barrier
	s_setprio 1
	s_waitcnt lgkmcnt(0)
	v_mfma_f32_16x16x32_bf16 v[50:53], v[146:149], v[178:181], v[50:53]
	v_mfma_f32_16x16x32_bf16 v[54:57], v[154:157], v[178:181], v[54:57]
	v_mfma_f32_16x16x32_bf16 v[34:37], v[146:149], v[186:189], v[34:37]
	v_mfma_f32_16x16x32_bf16 v[38:41], v[154:157], v[186:189], v[38:41]
	v_mfma_f32_16x16x32_bf16 v[18:21], v[146:149], v[202:205], v[18:21]
	v_mfma_f32_16x16x32_bf16 v[22:25], v[154:157], v[202:205], v[22:25]
	v_mfma_f32_16x16x32_bf16 v[2:5], v[146:149], v[210:213], v[2:5]
	v_mfma_f32_16x16x32_bf16 v[6:9], v[154:157], v[210:213], v[6:9]
	v_mfma_f32_16x16x32_bf16 v[50:53], v[150:153], v[182:185], v[50:53]
	v_mfma_f32_16x16x32_bf16 v[54:57], v[158:161], v[182:185], v[54:57]
	v_mfma_f32_16x16x32_bf16 v[34:37], v[150:153], v[190:193], v[34:37]
	v_mfma_f32_16x16x32_bf16 v[38:41], v[158:161], v[190:193], v[38:41]
	v_mfma_f32_16x16x32_bf16 v[18:21], v[150:153], v[206:209], v[18:21]
	v_mfma_f32_16x16x32_bf16 v[22:25], v[158:161], v[206:209], v[22:25]
	v_mfma_f32_16x16x32_bf16 v[2:5], v[150:153], v[214:217], v[2:5]
	v_mfma_f32_16x16x32_bf16 v[6:9], v[158:161], v[214:217], v[6:9]
	s_setprio 0
	s_setprio 1
	v_mfma_f32_16x16x32_bf16 v[58:61], v[162:165], v[178:181], v[58:61]
	v_mfma_f32_16x16x32_bf16 v[62:65], v[170:173], v[178:181], v[62:65]
	v_mfma_f32_16x16x32_bf16 v[42:45], v[162:165], v[186:189], v[42:45]
	v_mfma_f32_16x16x32_bf16 v[46:49], v[170:173], v[186:189], v[46:49]
	v_mfma_f32_16x16x32_bf16 v[26:29], v[162:165], v[202:205], v[26:29]
	v_mfma_f32_16x16x32_bf16 v[30:33], v[170:173], v[202:205], v[30:33]
	v_mfma_f32_16x16x32_bf16 v[10:13], v[162:165], v[210:213], v[10:13]
	v_mfma_f32_16x16x32_bf16 v[14:17], v[170:173], v[210:213], v[14:17]
	v_mfma_f32_16x16x32_bf16 v[58:61], v[166:169], v[182:185], v[58:61]
	v_mfma_f32_16x16x32_bf16 v[62:65], v[174:177], v[182:185], v[62:65]
	v_mfma_f32_16x16x32_bf16 v[42:45], v[166:169], v[190:193], v[42:45]
	v_mfma_f32_16x16x32_bf16 v[46:49], v[174:177], v[190:193], v[46:49]
	v_mfma_f32_16x16x32_bf16 v[26:29], v[166:169], v[206:209], v[26:29]
	v_mfma_f32_16x16x32_bf16 v[30:33], v[174:177], v[206:209], v[30:33]
	v_mfma_f32_16x16x32_bf16 v[10:13], v[166:169], v[214:217], v[10:13]
	v_mfma_f32_16x16x32_bf16 v[14:17], v[174:177], v[214:217], v[14:17]
	s_setprio 0
	s_barrier
	s_add_i32 s18, 0, 0x18000
	v_add_u32_e32 v145, s18, v141
	s_add_i32 s83, 0, 0x1c000
	ds_read_b128 v[146:149], v145
	ds_read_b128 v[150:153], v145 offset:1024
	ds_read_b128 v[154:157], v145 offset:2048
	ds_read_b128 v[158:161], v145 offset:3072
	v_add_u32_e32 v145, s83, v141
	ds_read_b128 v[162:165], v145
	ds_read_b128 v[166:169], v145 offset:1024
	ds_read_b128 v[170:173], v145 offset:2048
	ds_read_b128 v[174:177], v145 offset:3072
	s_add_u32 s38, s64, 0x40000
	s_addc_u32 s39, s65, 0
	s_mov_b32 m0, s58
	v_lshl_add_u64 v[224:225], s[38:39], 0, v[134:135]
	ds_read_b128 v[178:181], v144 offset:32768
	ds_read_b128 v[182:185], v144 offset:33792
	ds_read_b128 v[186:189], v144 offset:34816
	ds_read_b128 v[190:193], v144 offset:35840
	ds_read_b128 v[202:205], v144 offset:36864
	ds_read_b128 v[206:209], v144 offset:37888
	ds_read_b128 v[210:213], v144 offset:38912
	ds_read_b128 v[214:217], v144 offset:39936
	global_load_lds_dwordx4 v[224:225], off
	v_lshl_add_u64 v[224:225], s[38:39], 0, v[132:133]
	s_mov_b32 m0, s69
	s_nop 0
	global_load_lds_dwordx4 v[224:225], off
	s_waitcnt vmcnt(8)
	s_waitcnt lgkmcnt(0)
	s_barrier
	s_setprio 1
	s_waitcnt lgkmcnt(0)
	v_mfma_f32_16x16x32_bf16 v[114:117], v[146:149], v[178:181], v[114:117]
	v_mfma_f32_16x16x32_bf16 v[118:121], v[154:157], v[178:181], v[118:121]
	v_mfma_f32_16x16x32_bf16 v[98:101], v[146:149], v[186:189], v[98:101]
	v_mfma_f32_16x16x32_bf16 v[102:105], v[154:157], v[186:189], v[102:105]
	v_mfma_f32_16x16x32_bf16 v[82:85], v[146:149], v[202:205], v[82:85]
	v_mfma_f32_16x16x32_bf16 v[86:89], v[154:157], v[202:205], v[86:89]
	v_mfma_f32_16x16x32_bf16 v[66:69], v[146:149], v[210:213], v[66:69]
	v_mfma_f32_16x16x32_bf16 v[70:73], v[154:157], v[210:213], v[70:73]
	v_mfma_f32_16x16x32_bf16 v[114:117], v[150:153], v[182:185], v[114:117]
	v_mfma_f32_16x16x32_bf16 v[118:121], v[158:161], v[182:185], v[118:121]
	v_mfma_f32_16x16x32_bf16 v[98:101], v[150:153], v[190:193], v[98:101]
	v_mfma_f32_16x16x32_bf16 v[102:105], v[158:161], v[190:193], v[102:105]
	v_mfma_f32_16x16x32_bf16 v[82:85], v[150:153], v[206:209], v[82:85]
	v_mfma_f32_16x16x32_bf16 v[86:89], v[158:161], v[206:209], v[86:89]
	v_mfma_f32_16x16x32_bf16 v[66:69], v[150:153], v[214:217], v[66:69]
	v_mfma_f32_16x16x32_bf16 v[70:73], v[158:161], v[214:217], v[70:73]
	s_setprio 0
	s_setprio 1
	v_mfma_f32_16x16x32_bf16 v[122:125], v[162:165], v[178:181], v[122:125]
	v_mfma_f32_16x16x32_bf16 v[126:129], v[170:173], v[178:181], v[126:129]
	v_mfma_f32_16x16x32_bf16 v[106:109], v[162:165], v[186:189], v[106:109]
	v_mfma_f32_16x16x32_bf16 v[110:113], v[170:173], v[186:189], v[110:113]
	v_mfma_f32_16x16x32_bf16 v[90:93], v[162:165], v[202:205], v[90:93]
	v_mfma_f32_16x16x32_bf16 v[94:97], v[170:173], v[202:205], v[94:97]
	v_mfma_f32_16x16x32_bf16 v[74:77], v[162:165], v[210:213], v[74:77]
	v_mfma_f32_16x16x32_bf16 v[78:81], v[170:173], v[210:213], v[78:81]
	v_mfma_f32_16x16x32_bf16 v[122:125], v[166:169], v[182:185], v[122:125]
	v_mfma_f32_16x16x32_bf16 v[126:129], v[174:177], v[182:185], v[126:129]
	v_mfma_f32_16x16x32_bf16 v[106:109], v[166:169], v[190:193], v[106:109]
	v_mfma_f32_16x16x32_bf16 v[110:113], v[174:177], v[190:193], v[110:113]
	v_mfma_f32_16x16x32_bf16 v[90:93], v[166:169], v[206:209], v[90:93]
	v_mfma_f32_16x16x32_bf16 v[94:97], v[174:177], v[206:209], v[94:97]
	v_mfma_f32_16x16x32_bf16 v[74:77], v[166:169], v[214:217], v[74:77]
	v_mfma_f32_16x16x32_bf16 v[78:81], v[174:177], v[214:217], v[78:81]
	s_setprio 0
	s_barrier
; #define PG8_STAGE(bufoff, gbase, voff) do { _Pragma("unroll") for (int _i = 0; _i < 2; ++_i) \
;         __builtin_amdgcn_global_load_lds((const unsigned*)((const char*)(gbase) + (voff)[_i]), (PG8_LAS unsigned*)(lds + (bufoff) + ldsw + _i * 8192), 16, 0, 0); } while (0)
; #define PG8_LDA(dst, b, h) do { _Pragma("unroll") for (int m = 0; m < 4; ++m) _Pragma("unroll") for (int k = 0; k < 2; ++k) dst[m][k] = *(const PG8_LAS bf16x8*)(lds + PG8_SA(b, h) + aoff + m * 2048 + k * 1024); } while (0)
; #define PG8_MMA(ai, bj, At, Bt) do { __builtin_amdgcn_s_setprio(1); _Pragma("unroll") for (int m = 0; m < 4; ++m) _Pragma("unroll") for (int n = 0; n < 2; ++n) _Pragma("unroll") for (int k = 0; k < 2; ++k) \
;         acc[ai][bj][m][n] = __builtin_amdgcn_mfma_f32_16x16x32_bf16(Bt[n][k], At[m][k], acc[ai][bj][m][n], 0, 0, 0); __builtin_amdgcn_s_setprio(0); } while (0)
; #define PG8_WAIT_V(n) asm volatile("s_waitcnt vmcnt(" #n ")" ::: "memory")
; #define PG8_WAIT_L(n) asm volatile("s_waitcnt lgkmcnt(" #n ")" ::: "memory")
; #define PG8_BAR __builtin_amdgcn_s_barrier()
; #define PG8_SCHED __builtin_amdgcn_sched_barrier(0)
; template <class Epi, class Sched, bool ALIGN_EPI = false, bool SP2 = false>
; __device__ __forceinline__ void gemm_phase(PG8_LAS unsigned char* lds, const Gemm g, const Sched& S, const Epi& E) {
;     ...
;             PG8_LDA(At, 1, 1); PG8_STAGE(PG8_SB(1, 0), b3, voffB); PG8_STAGE(PG8_SB(1, 1), b3 + hstep, voffB); PG8_STAGE(PG8_SA(1, 0), a3, voffA);
;             PG8_WAIT_V(8); PG8_WAIT_L(0); PG8_BAR; PG8_MMA(1, 0, At, B0); PG8_MMA(1, 1, At, B1); PG8_BAR; PG8_SCHED;
;     ...
;         if constexpr (ALIGN_EPI) { if (wr == 0) PG8_BAR; }
;         if constexpr (!Epi::AFTER_DRAIN) { E(acc, cur, wr, wc, fr, fq, lds, rs_pm, rs_tog); S.done(cur); }
;         if (!has_next) break;
	s_add_i32 s18, s18, s27
	v_lshl_add_u64 v[194:195], v[194:195], 0, s[30:31]
	s_mov_b32 m0, s18
	ds_read_b128 v[178:181], v144 offset:49152
	ds_read_b128 v[182:185], v144 offset:50176
	ds_read_b128 v[186:189], v144 offset:51200
	ds_read_b128 v[190:193], v144 offset:52224
	ds_read_b128 v[202:205], v144 offset:53248
	ds_read_b128 v[206:209], v144 offset:54272
	ds_read_b128 v[210:213], v144 offset:55296
	ds_read_b128 v[214:217], v144 offset:56320
	global_load_lds_dwordx4 v[194:195], off
	s_add_i32 m0, s18, 0x2000
	s_add_u32 s38, s56, 0x40080
	v_lshl_add_u64 v[194:195], v[218:219], 0, s[30:31]
	s_addc_u32 s39, s57, 0
	s_add_i32 s18, s83, s27
	global_load_lds_dwordx4 v[194:195], off
	v_lshl_add_u64 v[194:195], s[38:39], 0, v[0:1]
	s_mov_b32 m0, s18
	s_nop 0
	global_load_lds_dwordx4 v[194:195], off
	v_lshl_add_u64 v[194:195], s[38:39], 0, v[130:131]
	s_add_i32 m0, s18, 0x2000
	s_nop 0
	global_load_lds_dwordx4 v[194:195], off
	v_lshl_add_u64 v[194:195], v[220:221], 0, s[30:31]
	s_mov_b32 m0, s71
	s_nop 0
	global_load_lds_dwordx4 v[194:195], off
	v_lshl_add_u64 v[194:195], v[222:223], 0, s[30:31]
	s_mov_b32 m0, s72
	s_nop 0
	global_load_lds_dwordx4 v[194:195], off
	s_waitcnt vmcnt(8)
	s_waitcnt lgkmcnt(0)
	s_barrier
	s_setprio 1
	s_waitcnt lgkmcnt(0)
	v_mfma_f32_16x16x32_bf16 v[50:53], v[146:149], v[178:181], v[50:53]
	v_mfma_f32_16x16x32_bf16 v[54:57], v[154:157], v[178:181], v[54:57]
	v_mfma_f32_16x16x32_bf16 v[34:37], v[146:149], v[186:189], v[34:37]
	v_mfma_f32_16x16x32_bf16 v[38:41], v[154:157], v[186:189], v[38:41]
	v_mfma_f32_16x16x32_bf16 v[18:21], v[146:149], v[202:205], v[18:21]
	v_mfma_f32_16x16x32_bf16 v[22:25], v[154:157], v[202:205], v[22:25]
	v_mfma_f32_16x16x32_bf16 v[2:5], v[146:149], v[210:213], v[2:5]
	v_mfma_f32_16x16x32_bf16 v[6:9], v[154:157], v[210:213], v[6:9]
	v_mfma_f32_16x16x32_bf16 v[50:53], v[150:153], v[182:185], v[50:53]
	v_mfma_f32_16x16x32_bf16 v[54:57], v[158:161], v[182:185], v[54:57]
	v_mfma_f32_16x16x32_bf16 v[34:37], v[150:153], v[190:193], v[34:37]
	v_mfma_f32_16x16x32_bf16 v[38:41], v[158:161], v[190:193], v[38:41]
	v_mfma_f32_16x16x32_bf16 v[18:21], v[150:153], v[206:209], v[18:21]
	v_mfma_f32_16x16x32_bf16 v[22:25], v[158:161], v[206:209], v[22:25]
	v_mfma_f32_16x16x32_bf16 v[2:5], v[150:153], v[214:217], v[2:5]
	v_mfma_f32_16x16x32_bf16 v[6:9], v[158:161], v[214:217], v[6:9]
	s_setprio 0
	s_setprio 1
	v_mfma_f32_16x16x32_bf16 v[58:61], v[162:165], v[178:181], v[58:61]
	v_mfma_f32_16x16x32_bf16 v[62:65], v[170:173], v[178:181], v[62:65]
	v_mfma_f32_16x16x32_bf16 v[42:45], v[162:165], v[186:189], v[42:45]
	v_mfma_f32_16x16x32_bf16 v[46:49], v[170:173], v[186:189], v[46:49]
	v_mfma_f32_16x16x32_bf16 v[26:29], v[162:165], v[202:205], v[26:29]
	v_mfma_f32_16x16x32_bf16 v[30:33], v[170:173], v[202:205], v[30:33]
	v_mfma_f32_16x16x32_bf16 v[10:13], v[162:165], v[210:213], v[10:13]
	v_mfma_f32_16x16x32_bf16 v[14:17], v[170:173], v[210:213], v[14:17]
	v_mfma_f32_16x16x32_bf16 v[58:61], v[166:169], v[182:185], v[58:61]
	v_mfma_f32_16x16x32_bf16 v[62:65], v[174:177], v[182:185], v[62:65]
	v_mfma_f32_16x16x32_bf16 v[42:45], v[166:169], v[190:193], v[42:45]
	v_mfma_f32_16x16x32_bf16 v[46:49], v[174:177], v[190:193], v[46:49]
	v_mfma_f32_16x16x32_bf16 v[26:29], v[166:169], v[206:209], v[26:29]
	v_mfma_f32_16x16x32_bf16 v[30:33], v[174:177], v[206:209], v[30:33]
	v_mfma_f32_16x16x32_bf16 v[10:13], v[166:169], v[214:217], v[10:13]
	v_mfma_f32_16x16x32_bf16 v[14:17], v[174:177], v[214:217], v[14:17]
	s_setprio 0
	s_barrier
	s_add_i32 s82, s82, 2
	s_add_u32 s60, s60, 0x100
	s_addc_u32 s61, s61, 0
	s_add_u32 s80, s80, 0x100
	s_addc_u32 s81, s81, 0
	s_cmp_gt_u32 s82, 13
	s_cbranch_scc0 .LBB0_220
	s_cmp_lg_u32 s77, s75
	s_cbranch_scc1 .Ldef_no
	s_and_b64 vcc, exec, s[42:43]
	s_cbranch_vccz .Ldef_no
	s_mov_b32 s100, s76
	s_mov_b32 s101, 1
	s_branch .LBB0_215
.Ldef_no:
	s_and_b64 vcc, exec, s[44:45]
	s_cbranch_vccz .LBB0_223
	s_barrier

; __global__ void __launch_bounds__(NTHREADS, 2) fwd_megakernel(Args args) {
	.amdhsa_kernel _Z14fwd_megakernel4Args
		.amdhsa_group_segment_fixed_size 0
		.amdhsa_private_segment_fixed_size 0
		.amdhsa_kernarg_size 408
		.amdhsa_user_sgpr_count 2
		.amdhsa_user_sgpr_dispatch_ptr 0
		.amdhsa_user_sgpr_queue_ptr 0
		.amdhsa_user_sgpr_kernarg_segment_ptr 1
		.amdhsa_user_sgpr_dispatch_id 0
		.amdhsa_user_sgpr_kernarg_preload_length 0
		.amdhsa_user_sgpr_kernarg_preload_offset 0
		.amdhsa_user_sgpr_private_segment_size 0
		.amdhsa_uses_dynamic_stack 0
		.amdhsa_enable_private_segment 0
		.amdhsa_system_sgpr_workgroup_id_x 1
		.amdhsa_system_sgpr_workgroup_id_y 0
		.amdhsa_system_sgpr_workgroup_id_z 0
		.amdhsa_system_sgpr_workgroup_info 0
		.amdhsa_system_vgpr_workitem_id 2
		.amdhsa_next_free_vgpr 255
		.amdhsa_next_free_sgpr 102
		.amdhsa_accum_offset 256
		.amdhsa_reserve_vcc 1
		.amdhsa_float_round_mode_32 0
		.amdhsa_float_round_mode_16_64 0
		.amdhsa_float_denorm_mode_32 3
		.amdhsa_float_denorm_mode_16_64 3
		.amdhsa_dx10_clamp 1
		.amdhsa_ieee_mode 1
		.amdhsa_fp16_overflow 0
		.amdhsa_tg_split 0
		.amdhsa_exception_fp_ieee_invalid_op 0
		.amdhsa_exception_fp_denorm_src 0
		.amdhsa_exception_fp_ieee_div_zero 0
		.amdhsa_exception_fp_ieee_overflow 0
		.amdhsa_exception_fp_ieee_underflow 0
		.amdhsa_exception_fp_ieee_inexact 0
		.amdhsa_exception_int_div_zero 0
	.end_amdhsa_kernel

; __global__ void __launch_bounds__(NTHREADS, 2) fwd_megakernel(Args args) {
amdhsa.kernels:
  - .agpr_count:     0
    .args:
      - .offset:         0
        .size:           152
        .value_kind:     by_value
      - .offset:         152
        .size:           4
        .value_kind:     hidden_block_count_x
      - .offset:         156
        .size:           4
        .value_kind:     hidden_block_count_y
      - .offset:         160
        .size:           4
        .value_kind:     hidden_block_count_z
      - .offset:         164
        .size:           2
        .value_kind:     hidden_group_size_x
      - .offset:         166
        .size:           2
        .value_kind:     hidden_group_size_y
      - .offset:         168
        .size:           2
        .value_kind:     hidden_group_size_z
      - .offset:         170
        .size:           2
        .value_kind:     hidden_remainder_x
      - .offset:         172
        .size:           2
        .value_kind:     hidden_remainder_y
      - .offset:         174
        .size:           2
        .value_kind:     hidden_remainder_z
      - .offset:         192
        .size:           8
        .value_kind:     hidden_global_offset_x
      - .offset:         200
        .size:           8
        .value_kind:     hidden_global_offset_y
      - .offset:         208
        .size:           8
        .value_kind:     hidden_global_offset_z
      - .offset:         216
        .size:           2
        .value_kind:     hidden_grid_dims
      - .offset:         240
        .size:           8
        .value_kind:     hidden_multigrid_sync_arg
      - .offset:         272
        .size:           4
        .value_kind:     hidden_dynamic_lds_size
    .group_segment_fixed_size: 0
    .kernarg_segment_align: 8
    .kernarg_segment_size: 408
    .language:       OpenCL C
    .language_version:
      - 2
      - 0
    .max_flat_workgroup_size: 512
    .name:           _Z14fwd_megakernel4Args
    .private_segment_fixed_size: 0
    .sgpr_count:     108
    .sgpr_spill_count: 146
    .symbol:         _Z14fwd_megakernel4Args.kd
    .uniform_work_group_size: 1
    .uses_dynamic_stack: false
    .vgpr_count:     255
    .vgpr_spill_count: 0
    .wavefront_size: 64
